# sample-row completion counter: one atomic per workgroup after the proj_res barrier instead of one per storing wave
# baseline (speedup 1.0000x reference)
.LBB0_1134:
	s_barrier
	s_and_saveexec_b64 s[6:7], s[94:95]
	v_mov_b32_e32 v4, 1
	v_mov_b32_e32 v5, 0x27100
	global_atomic_add v5, v4, s[68:69]
	s_mov_b64 exec, s[6:7]
	global_load_dword v160, v3, s[68:69] sc1
	s_cmpk_gt_i32 s12, 0xff
	s_nop 0
	v_readfirstlane_b32 s15, v0
	s_cbranch_scc1 .LBB0_1197
	v_lshlrev_b32_e32 v1, 4, v0
	v_add_u32_e32 v2, 0x2000, v1
	v_ashrrev_i32_e32 v3, 31, v2
	v_lshrrev_b32_e32 v3, 22, v3
	v_add_u32_e32 v3, v2, v3
	v_ashrrev_i32_e32 v10, 10, v3
	v_mul_i32_i24_e32 v3, 0x400, v10
	s_ashr_i32 s7, s12, 31
	v_sub_u32_e32 v2, v2, v3
	s_lshr_b32 s1, s7, 29
	v_lshrrev_b32_e32 v3, 4, v2
	s_add_i32 s1, s12, s1
	v_bitop3_b32 v2, v3, v2, 32 bitop3:0x6c
	s_ashr_i32 s2, s1, 3
	s_and_b32 s1, s1, -8
	s_ashr_i32 s9, s15, 6
	v_ashrrev_i32_e32 v3, 31, v2
	s_sub_i32 s1, s12, s1
	s_ashr_i32 s13, s15, 8
	s_lshl_b32 s6, s9, 10
	v_lshrrev_b32_e32 v3, 26, v3
	s_lshl_b32 s4, s1, 5
	v_add_u32_e32 v3, v2, v3
	s_mul_i32 s3, s1, 33
	s_cmp_lt_i32 s1, 0
	v_ashrrev_i32_e32 v11, 6, v3
	v_and_b32_e32 v3, 0xc0, v3
	s_cselect_b32 s1, s3, s4
	v_sub_u32_e32 v2, v2, v3
	v_mov_b32_e32 v3, 1
	s_add_i32 s1, s1, s2
	v_ashrrev_i16_sdwa v2, v3, sext(v2) dst_sel:DWORD dst_unused:UNUSED_PAD src0_sel:DWORD src1_sel:BYTE_0
	s_ashr_i32 s2, s1, 31
	v_lshlrev_b32_e32 v4, 3, v10
	v_bfe_i32 v13, v2, 0, 16
	v_bfe_i32 v2, v0, 27, 1
	s_lshr_b32 s2, s2, 27
	v_and_b32_e32 v4, 0xfffff0, v4
	v_lshrrev_b32_e32 v2, 22, v2
	s_add_i32 s2, s1, s2
	v_add_u32_e32 v4, v11, v4
	s_movk_i32 s0, 0xb00
	v_lshlrev_b32_e32 v5, 5, v10
	v_add_u32_e32 v2, v1, v2
	s_ashr_i32 s3, s2, 5
	s_and_b32 s2, s2, 0xffe0
	v_mul_lo_u32 v4, v4, s0
	v_and_b32_e32 v12, 32, v5
	v_and_b32_e32 v2, 0xfffffc00, v2
	s_sub_i32 s2, s1, s2
	v_or_b32_e32 v4, v4, v12
	v_sub_u32_e32 v1, v1, v2
	s_bfe_i32 s1, s2, 0x80000
	v_add_lshl_u32 v130, v4, v13, 1
	v_lshrrev_b32_e32 v2, 4, v1
	v_ashrrev_i32_e32 v4, 31, v0
	s_bfe_u32 s1, s1, 0x3000c
	v_bitop3_b32 v1, v2, v1, 32 bitop3:0x6c
	v_lshrrev_b32_e32 v4, 26, v4
	s_add_i32 s4, s2, s1
	v_ashrrev_i32_e32 v2, 31, v1
	v_add_u32_e32 v4, v0, v4
	s_bfe_i32 s1, s4, 0x80000
	s_and_b32 s4, s4, 0xf8
	v_lshrrev_b32_e32 v2, 26, v2
	v_ashrrev_i32_e32 v15, 6, v4
	s_sub_i32 s2, s2, s4
	v_add_u32_e32 v2, v1, v2
	v_lshlrev_b32_e32 v4, 3, v15
	s_lshl_b32 s3, s3, 3
	s_sext_i32_i16 s5, s1
	s_sext_i32_i8 s2, s2
	v_ashrrev_i32_e32 v14, 6, v2
	v_and_b32_e32 v4, 0xfffff0, v4
	v_and_b32_e32 v2, 0xc0, v2
	s_add_i32 s35, s3, s2
	s_ashr_i32 s2, s5, 3
	v_add_u32_e32 v4, v14, v4
	v_lshlrev_b32_e32 v5, 5, v15
	v_sub_u32_e32 v1, v1, v2
	s_lshr_b32 s1, s5, 3
	s_mul_hi_i32 s3, s2, 0x160000
	s_mul_i32 s2, s2, 0x160000
	v_mul_lo_u32 v4, v4, s0
	v_and_b32_e32 v16, 32, v5
	v_ashrrev_i16_sdwa v1, v3, sext(v1) dst_sel:DWORD dst_unused:UNUSED_PAD src0_sel:DWORD src1_sel:BYTE_0
	s_add_u32 s22, s97, s2
	v_or_b32_e32 v4, v4, v16
	v_bfe_i32 v17, v1, 0, 16
	s_addc_u32 s23, s20, s3
	s_add_i32 s26, s6, 0
	v_add_lshl_u32 v132, v4, v17, 1
	s_add_i32 m0, s26, 0x10000
	s_mul_i32 s8, s35, 0x160000
	global_load_lds_dwordx4 v132, s[22:23]
	s_add_i32 m0, s26, 0x12000
	s_add_u32 s2, s22, 0xb0000
	global_load_lds_dwordx4 v130, s[22:23]
	s_addc_u32 s3, s23, 0
	s_add_i32 m0, s26, 0x14000
	s_mul_hi_i32 s4, s35, 0x160000
	global_load_lds_dwordx4 v132, s[2:3]
	s_add_i32 m0, s26, 0x16000
	s_add_u32 s10, s36, s8
	s_addc_u32 s11, s37, s4
	s_add_i32 s27, s26, 0x2000
	global_load_lds_dwordx4 v130, s[2:3]
	s_mov_b32 m0, s26
	s_add_u32 s2, s10, 0xb0000
	global_load_lds_dwordx4 v132, s[10:11]
	s_mov_b32 m0, s27
	s_addc_u32 s3, s11, 0
	s_add_i32 s29, s26, 0x4000
	global_load_lds_dwordx4 v130, s[10:11]
	s_mov_b32 m0, s29
	s_add_i32 s30, s26, 0x6000
	global_load_lds_dwordx4 v132, s[2:3]
	s_mov_b32 m0, s30
	v_mov_b32_e32 v133, 0
	global_load_lds_dwordx4 v130, s[2:3]
	v_mov_b32_e32 v131, v133
	s_mov_b32 s31, 0
	v_lshl_add_u64 v[8:9], s[22:23], 0, v[132:133]
	v_lshl_add_u64 v[6:7], s[22:23], 0, v[130:131]
	v_lshl_add_u64 v[4:5], s[10:11], 0, v[132:133]
	s_cmp_lg_u32 s13, 1
	v_lshl_add_u64 v[2:3], s[10:11], 0, v[130:131]
	s_cbranch_scc1 .LBB0_1137
	s_barrier

.Lp8_spin:
	global_load_dword v2, v1, s[68:69] sc1
	s_waitcnt vmcnt(0)
	v_readfirstlane_b32 s1, v2
	s_cmpk_lt_u32 s1, 0x100
	s_cbranch_scc0 .Lp8_ok
	s_sleep 2
	s_add_i32 s0, s0, 1
	s_cmp_lt_u32 s0, 0x100000
	s_cbranch_scc1 .Lp8_spin
